# bias scan: DPP row_shr/row_bcast wave scan + parallel cross-wave LDS reads instead of serial bpermute/read chains, on e8rd2
# baseline (speedup 1.0000x reference)
; __device__ __forceinline__ void bias_scan(char*shm,const float*__restrict__ lf,float*gdst=nullptr){
;   const int tid=threadIdx.x,lane=tid&63,wid=tid>>6;
;   float*bias=(float*)(shm+LDS_BIAS); float*wtot=(float*)(shm+LDS_WS);
;   const f32x4v a=*(const f32x4v*)(lf+tid*8),b=*(const f32x4v*)(lf+tid*8+4);
;   const float s0=a[0],s1=s0+a[1],s2=s1+a[2],s3=s2+a[3],s4=s3+b[0],s5=s4+b[1],s6=s5+b[2],s7=s6+b[3];
;   float inc=s7;
;   #pragma unroll
;   for(int o=1;o<64;o<<=1){const float t=__shfl_up(inc,o); if(lane>=o)inc+=t;}
;   if(lane==63)wtot[wid]=inc;
;   asm volatile("s_waitcnt lgkmcnt(0)\n\ts_barrier":::"memory");
;   float base=0.f;
;   #pragma unroll
;   for(int w=0;w<NW;++w){const float x=wtot[w]; if(w<wid)base+=x;}
;   const float off=base+inc-s7; const float NL=-1.4426950408889634f;
;   *(f32x4v*)(bias+tid*8)=(f32x4v){(off+s0)*NL,(off+s1)*NL,(off+s2)*NL,(off+s3)*NL};
;   *(f32x4v*)(bias+tid*8+4)=(f32x4v){(off+s4)*NL,(off+s5)*NL,(off+s6)*NL,(off+s7)*NL};
;   if(gdst){ *(f32x4v*)(gdst+tid*8)=(f32x4v){(off+s0)*NL,(off+s1)*NL,(off+s2)*NL,(off+s3)*NL}; *(f32x4v*)(gdst+tid*8+4)=(f32x4v){(off+s4)*NL,(off+s5)*NL,(off+s6)*NL,(off+s7)*NL}; }
;   asm volatile("s_waitcnt lgkmcnt(0)\n\ts_barrier":::"memory");
; }
; __device__ __forceinline__ void j0_table(const char*shm,float gap,int*dst,int wave,int lane){
;   const __attribute__((address_space(3))) float*bl=(const __attribute__((address_space(3))) float*)((const __attribute__((address_space(3))) char*)shm+LDS_BIAS);
;   const float v=bl[64*lane+63];
;   #pragma unroll
;   for(int q=0;q<2;++q){ const int qb=2*wave+q; const float thr=bl[QB*qb]-gap; const unsigned long long mk=__ballot(v>=thr);
;     int j0=mk?(int)__builtin_ctzll(mk):0; j0&=~1; const int jmax=4*qb; j0=j0<jmax?j0:jmax; if(lane==0)dst[qb]=j0; }
; __device__ __forceinline__ float qk_bound(const float* q_g, const float* k_g, int lane) {
;     float gq = fabsf(q_g[lane]), gk = fabsf(k_g[lane]);
; #pragma unroll
;     for (int o = 1; o < 64; o <<= 1) { gq = fmaxf(gq, __shfl_xor(gq, o)); gk = fmaxf(gk, __shfl_xor(gk, o)); }
;     return attn_body::C2 * 64.0f * 1.02f * gq * gk;
.LBB0_199:
	s_or_b64 exec, exec, s[4:5]
	s_mov_b64 s[4:5], s[0:1]
	s_waitcnt lgkmcnt(0)
	s_barrier
	v_mov_b32_e32 v12, v0
	s_mov_b32 s14, s2
	s_load_dwordx4 s[8:11], s[4:5], 0x38
	s_load_dwordx2 s[12:13], s[4:5], 0x70
	s_load_dword s3, s[24:25], 0x0
	v_lshlrev_b32_e32 v170, 3, v0
	v_mov_b32_e32 v7, 0
	v_readfirstlane_b32 s16, v12
	s_cmp_gt_i32 s14, 63
	s_waitcnt lgkmcnt(0)
	s_mov_b32 s29, s3
	v_and_b32_e32 v1, 63, v0
	s_cbranch_scc1 .LBB0_223
	s_ashr_i32 s15, s14, 31
	s_lshl_b64 s[4:5], s[14:15], 14
	s_add_u32 s4, s12, s4
	s_addc_u32 s5, s13, s5
	v_lshlrev_b32_e32 v6, 2, v170
	v_lshl_add_u64 v[8:9], s[4:5], 0, v[6:7]
	s_mov_b32 s4, 0x100000
	v_add_co_u32_e32 v2, vcc, s4, v8
	s_mov_b64 s[4:5], 0x100000
	s_nop 0
	v_addc_co_u32_e32 v3, vcc, 0, v9, vcc
	global_load_dwordx4 v[2:5], v[2:3], off
	v_lshl_add_u64 v[8:9], v[8:9], 0, s[4:5]
	global_load_dwordx4 v[14:17], v[8:9], off offset:16
	s_waitcnt vmcnt(1)
	v_add_f32_e32 v3, v2, v3
	v_add_f32_e32 v10, v4, v3
	v_add_f32_e32 v11, v5, v10
	s_waitcnt vmcnt(0)
	v_add_f32_e32 v8, v14, v11
	v_add_f32_e32 v9, v15, v8
	v_add_f32_e32 v4, v16, v9
	v_add_f32_e32 v5, v17, v4
	v_mov_b32_e32 v7, v5
	s_nop 1
	v_add_f32_dpp v7, v7, v7 row_shr:1 row_mask:0xf bank_mask:0xf
	s_nop 1
	v_add_f32_dpp v7, v7, v7 row_shr:2 row_mask:0xf bank_mask:0xf
	s_nop 1
	v_add_f32_dpp v7, v7, v7 row_shr:4 row_mask:0xf bank_mask:0xf
	s_nop 1
	v_add_f32_dpp v7, v7, v7 row_shr:8 row_mask:0xf bank_mask:0xf
	s_nop 1
	v_add_f32_dpp v7, v7, v7 row_bcast:15 row_mask:0xa bank_mask:0xf
	s_nop 1
	v_add_f32_dpp v7, v7, v7 row_bcast:31 row_mask:0xc bank_mask:0xf
	v_cmp_eq_u32_e32 vcc, 63, v1
	v_mov_b32_e32 v13, v7
	s_and_saveexec_b64 s[4:5], vcc
	v_lshrrev_b32_e32 v14, 4, v0
	v_and_b32_e32 v14, 28, v14
	v_add_u32_e32 v14, 0, v14
	ds_write_b32 v14, v13 offset:49152
	s_or_b64 exec, exec, s[4:5]
	s_waitcnt lgkmcnt(0)
	s_barrier
	v_mov_b32_e32 v15, 0
	ds_read_b128 v[20:23], v15 offset:49152
	ds_read_b128 v[24:27], v15 offset:49168
	v_mov_b32_e32 v14, 0
	s_lshl_b64 s[4:5], s[14:15], 12
	s_waitcnt lgkmcnt(0)
	v_cmp_lt_u32_e32 vcc, 63, v0
	v_cndmask_b32_e32 v15, 0, v20, vcc
	v_add_f32_e32 v14, v14, v15
	v_cmp_lt_u32_e32 vcc, 0x7f, v0
	v_cndmask_b32_e32 v15, 0, v21, vcc
	v_add_f32_e32 v14, v14, v15
	v_cmp_lt_u32_e32 vcc, 0xbf, v0
	v_cndmask_b32_e32 v15, 0, v22, vcc
	v_add_f32_e32 v14, v14, v15
	v_cmp_lt_u32_e32 vcc, 0xff, v0
	v_cndmask_b32_e32 v15, 0, v23, vcc
	v_add_f32_e32 v14, v14, v15
	v_cmp_lt_u32_e32 vcc, 0x13f, v0
	v_cndmask_b32_e32 v15, 0, v24, vcc
	v_add_f32_e32 v14, v14, v15
	v_cmp_lt_u32_e32 vcc, 0x17f, v0
	v_cndmask_b32_e32 v15, 0, v25, vcc
	v_add_f32_e32 v14, v14, v15
	v_cmp_lt_u32_e32 vcc, 0x1bf, v0
	v_cndmask_b32_e32 v15, 0, v26, vcc
	v_add_f32_e32 v14, v14, v15
	v_cmp_lt_u32_e32 vcc, 0x1ff, v0
	v_cndmask_b32_e32 v15, 0, v27, vcc
	v_add_f32_e32 v14, v14, v15
	s_lshl_b64 s[4:5], s[4:5], 2
	v_cmp_gt_u32_e32 vcc, 32, v1
	s_add_u32 s4, s12, s4
	s_addc_u32 s5, s13, s5
	v_cndmask_b32_e32 v7, v13, v7, vcc
	s_add_i32 s17, 0, 0x14800
	v_add_f32_e32 v7, v7, v14
	v_lshl_add_u32 v15, v170, 2, s17
	v_sub_f32_e32 v14, v7, v5
	v_pk_add_f32 v[2:3], v[2:3], v[14:15] op_sel_hi:[1,0]
	v_pk_add_f32 v[10:11], v[10:11], v[14:15] op_sel_hi:[1,0]
	s_mov_b32 s6, 0xbfb8aa3b
	v_and_b32_e32 v16, 63, v12
	v_pk_mul_f32 v[12:13], v[10:11], s[6:7] op_sel_hi:[1,0]
	v_pk_mul_f32 v[10:11], v[2:3], s[6:7] op_sel_hi:[1,0]
	v_pk_add_f32 v[2:3], v[8:9], v[14:15] op_sel_hi:[1,0]
	v_pk_add_f32 v[4:5], v[4:5], v[14:15] op_sel_hi:[1,0]
	v_mov_b32_e32 v7, 0
	v_pk_mul_f32 v[4:5], v[4:5], s[6:7] op_sel_hi:[1,0]
	v_pk_mul_f32 v[2:3], v[2:3], s[6:7] op_sel_hi:[1,0]
	v_lshl_add_u64 v[8:9], s[4:5], 0, v[6:7]
	s_mov_b64 s[4:5], 0x1c000000
	ds_write_b128 v15, v[10:13]
	ds_write_b128 v15, v[2:5] offset:16
	v_lshl_add_u64 v[14:15], v[8:9], 0, s[4:5]
	s_brev_b32 s4, 56
	v_add_co_u32_e32 v8, vcc, s4, v8
	s_lshl_b32 s4, s14, 4
	s_nop 0
	v_addc_co_u32_e32 v9, vcc, 0, v9, vcc
	global_store_dwordx4 v[8:9], v[10:13], off
	global_store_dwordx4 v[14:15], v[2:5], off offset:16
	s_waitcnt lgkmcnt(0)
	s_barrier
	s_ashr_i32 s5, s4, 31
	s_ashr_i32 s7, s16, 6
	v_lshlrev_b32_e32 v2, 2, v16
	global_load_dword v3, v2, s[8:9]
	global_load_dword v4, v2, s[10:11]
	s_lshl_b64 s[4:5], s[4:5], 2
	s_add_u32 s4, s12, s4
	s_addc_u32 s5, s13, s5
	s_add_u32 s15, s4, 0x1c100000
	s_addc_u32 s20, s5, 0
	s_lshl_b32 s4, s7, 11
	v_lshl_add_u32 v6, v16, 8, s17
	s_add_i32 s4, s17, s4
	v_mov_b32_e32 v9, s4
	s_lshl_b32 s6, s7, 1
	v_cmp_eq_u32_e32 vcc, 0, v16
	s_waitcnt vmcnt(1)
	v_and_b32_e32 v2, 0x7fffffff, v3
	s_waitcnt vmcnt(0)
	v_and_b32_e32 v5, 0x7fffffff, v4
	ds_bpermute_b32 v2, v165, v2
	ds_bpermute_b32 v5, v165, v5
	v_max_f32_e64 v3, |v3|, |v3|
	v_max_f32_e64 v4, |v4|, |v4|
	s_waitcnt lgkmcnt(1)
	v_max_f32_e32 v2, v2, v2
	s_waitcnt lgkmcnt(0)
	v_max_f32_e32 v5, v5, v5
	v_max_f32_e32 v2, v3, v2
	v_max_f32_e32 v3, v4, v5
	ds_bpermute_b32 v4, v169, v2
	ds_bpermute_b32 v5, v169, v3
	s_waitcnt lgkmcnt(1)
	v_max_f32_e32 v4, v4, v4
	s_waitcnt lgkmcnt(0)
	v_max_f32_e32 v5, v5, v5
	v_max_f32_e32 v2, v2, v4
	v_max_f32_e32 v3, v3, v5
	ds_bpermute_b32 v4, v168, v2
	ds_bpermute_b32 v5, v168, v3
	s_waitcnt lgkmcnt(1)
	v_max_f32_e32 v4, v4, v4
	s_waitcnt lgkmcnt(0)
	v_max_f32_e32 v5, v5, v5
	v_max_f32_e32 v2, v2, v4
	v_max_f32_e32 v3, v3, v5
	ds_bpermute_b32 v4, v167, v2
	ds_bpermute_b32 v5, v167, v3
	s_waitcnt lgkmcnt(1)
	v_max_f32_e32 v4, v4, v4
	s_waitcnt lgkmcnt(0)
	v_max_f32_e32 v5, v5, v5
	v_max_f32_e32 v2, v2, v4
	v_max_f32_e32 v3, v3, v5
	ds_bpermute_b32 v4, v166, v2
	ds_bpermute_b32 v5, v166, v3
	s_waitcnt lgkmcnt(1)
	v_max_f32_e32 v4, v4, v4
	s_waitcnt lgkmcnt(0)
	v_max_f32_e32 v5, v5, v5
	v_max_f32_e32 v4, v2, v4
	v_max_f32_e32 v3, v3, v5
	ds_bpermute_b32 v5, v164, v4
	ds_bpermute_b32 v8, v164, v3
	ds_read_b32 v2, v6 offset:252
	ds_read_b32 v6, v9
	s_waitcnt lgkmcnt(3)
	v_max_f32_e32 v5, v5, v5
	s_waitcnt lgkmcnt(2)
	v_max_f32_e32 v8, v8, v8
	v_max_f32_e32 v4, v4, v5
	v_max_f32_e32 v3, v3, v8
	v_mul_f32_e32 v4, 0x413c5bb7, v4
	v_mul_f32_e32 v3, v4, v3
	v_fmaak_f32 v3, 2.0, v3, 0x42180000
	s_waitcnt lgkmcnt(0)
	v_sub_f32_e32 v4, v6, v3
	v_cmp_ge_f32_e64 s[4:5], v2, v4
	s_and_saveexec_b64 s[16:17], vcc
	s_cbranch_execz .LBB0_220
	s_ff1_i32_b64 s21, s[4:5]
	s_and_b32 s21, s21, 62
	s_cmp_lg_u64 s[4:5], 0
	s_cselect_b32 s4, s21, 0
	s_lshl_b32 s5, s7, 3
	s_ashr_i32 s7, s6, 31
	s_min_i32 s21, s4, s5
	s_lshl_b64 s[4:5], s[6:7], 2
	s_add_u32 s4, s15, s4
	s_addc_u32 s5, s20, s5
	v_mov_b32_e32 v4, s21
	global_store_dword v7, v4, s[4:5]
